# MLA loop s_setprio 1 for waves with low block idx (vs v059)
# baseline (speedup 1.0000x reference)
.LBB0_2190:
	v_and_b32_e32 v50, 63, v192
	v_lshlrev_b32_e32 v52, 4, v50
	v_lshlrev_b32_e32 v51, 3, v50
	v_and_b32_e32 v52, 0xc0, v52
	v_lshlrev_b32_e32 v53, 1, v50
	v_and_or_b32 v52, v51, 24, v52
	v_and_b32_e32 v53, 32, v53
	v_and_b32_e32 v51, 0x100, v51
	v_or3_b32 v51, v52, v53, v51
	v_add_u32_e32 v209, 0, v51
	v_max_f32_e32 v51, v35, v35
	v_max_f32_e32 v52, v34, v34
	v_max_f32_e32 v51, v52, v51
	v_max3_f32 v51, v51, v36, v37
	v_max3_f32 v51, v51, v38, v39
	v_max3_f32 v51, v51, v40, v41
	v_max3_f32 v51, v51, v42, v43
	v_max3_f32 v51, v51, v44, v45
	v_max3_f32 v51, v51, v46, v47
	v_max3_f32 v51, v51, v48, v49
	v_max3_f32 v51, v51, v18, v19
	v_max3_f32 v51, v51, v20, v21
	v_max3_f32 v51, v51, v22, v23
	v_max3_f32 v51, v51, v24, v25
	v_max3_f32 v51, v51, v26, v27
	v_max3_f32 v51, v51, v28, v29
	v_max3_f32 v51, v51, v30, v31
	v_max3_f32 v51, v51, v32, v33
	v_mov_b32_e32 v52, v51
	s_nop 1
	v_permlane32_swap_b32_e32 v51, v52
	v_max_f32_e32 v52, v52, v52
	v_max_f32_e32 v51, v51, v51
	s_lshl_b32 s1, s1, 8
	v_max_f32_e32 v51, v51, v52
	s_lshl_b32 s0, s0, 2
	s_add_i32 s10, s1, 0
	v_add_f32_e32 v52, 0x7149f2ca, v51
	s_sub_i32 s21, 0x100, s0
	s_add_i32 s10, s10, 0x18000
	s_add_i32 s11, s11, -2.0
	v_cmp_ge_f32_e32 vcc, s83, v52
	v_max_f32_e32 v51, 0xf149f2ca, v51
	s_cmp_eq_u64 vcc, exec
	v_sub_f32_e32 v53, 0xf149f2ca, v51
	s_cselect_b64 vcc, -1, 0
	v_exp_f32_e32 v53, v53
	v_cndmask_b32_e32 v238, v51, v199, vcc
	v_sub_f32_e32 v34, v34, v238
	v_sub_f32_e32 v35, v35, v238
	v_sub_f32_e32 v36, v36, v238
	v_sub_f32_e32 v37, v37, v238
	v_sub_f32_e32 v38, v38, v238
	v_sub_f32_e32 v39, v39, v238
	v_sub_f32_e32 v40, v40, v238
	v_sub_f32_e32 v41, v41, v238
	v_sub_f32_e32 v42, v42, v238
	v_sub_f32_e32 v43, v43, v238
	v_sub_f32_e32 v44, v44, v238
	v_sub_f32_e32 v45, v45, v238
	v_sub_f32_e32 v46, v46, v238
	v_sub_f32_e32 v47, v47, v238
	v_sub_f32_e32 v48, v48, v238
	v_sub_f32_e32 v49, v49, v238
	v_exp_f32_e32 v82, v34
	v_exp_f32_e32 v83, v35
	v_exp_f32_e32 v84, v36
	v_exp_f32_e32 v85, v37
	v_exp_f32_e32 v86, v38
	v_exp_f32_e32 v87, v39
	v_exp_f32_e32 v88, v40
	v_exp_f32_e32 v89, v41
	v_exp_f32_e32 v90, v42
	v_exp_f32_e32 v91, v43
	v_exp_f32_e32 v92, v44
	v_exp_f32_e32 v93, v45
	v_exp_f32_e32 v94, v46
	v_exp_f32_e32 v95, v47
	v_exp_f32_e32 v96, v48
	v_exp_f32_e32 v97, v49
	s_add_i32 s2, s6, 0x3e45
	v_sub_f32_e32 v98, v18, v238
	s_waitcnt vmcnt(0)
	s_sub_i32 s22, 0xff, s0
	v_cmp_gt_u32_e64 s[0:1], 32, v50
	v_add_u32_e32 v18, s2, v14
	v_mov_b32_e32 v50, v1
	v_mov_b32_e32 v51, v1
	v_mov_b32_e32 v64, v1
	v_mov_b32_e32 v65, v1
	v_cndmask_b32_e64 v236, v53, 1.0, vcc
	v_sub_f32_e32 v113, v33, v238
	v_sub_f32_e32 v112, v32, v238
	v_sub_f32_e32 v111, v31, v238
	v_sub_f32_e32 v110, v30, v238
	v_sub_f32_e32 v109, v29, v238
	v_sub_f32_e32 v108, v28, v238
	v_sub_f32_e32 v107, v27, v238
	v_sub_f32_e32 v106, v26, v238
	v_sub_f32_e32 v105, v25, v238
	v_sub_f32_e32 v104, v24, v238
	v_sub_f32_e32 v103, v23, v238
	v_sub_f32_e32 v102, v22, v238
	v_sub_f32_e32 v101, v21, v238
	v_sub_f32_e32 v100, v20, v238
	v_sub_f32_e32 v99, v19, v238
	v_lshl_add_u32 v227, v17, 2, s10
	v_sub_u32_e32 v17, v18, v17
	v_mov_b32_e32 v52, v1
	v_mov_b32_e32 v53, v1
	v_mov_b32_e32 v54, v1
	v_mov_b32_e32 v55, v1
	v_mov_b32_e32 v56, v1
	v_mov_b32_e32 v57, v1
	v_mov_b32_e32 v58, v1
	v_mov_b32_e32 v59, v1
	v_mov_b32_e32 v60, v1
	v_mov_b32_e32 v61, v1
	v_mov_b32_e32 v62, v1
	v_mov_b32_e32 v63, v1
	v_mov_b64_e32 v[80:81], v[64:65]
	v_mov_b64_e32 v[34:35], v[50:51]
	v_mov_b64_e32 v[18:19], v[50:51]
	v_mov_b32_e32 v211, v1
	v_mov_b32_e32 v213, v1
	v_mov_b32_e32 v215, v1
	v_mov_b32_e32 v217, v1
	s_mov_b32 s20, 2
	v_lshl_add_u32 v228, v14, 2, s10
	v_subrev_u32_e32 v237, s8, v17
	s_mov_b32 s26, 0
	v_mov_b32_e32 v17, 0
	s_movk_i32 s23, 0xbf
	v_mov_b64_e32 v[78:79], v[62:63]
	v_mov_b64_e32 v[76:77], v[60:61]
	v_mov_b64_e32 v[74:75], v[58:59]
	v_mov_b64_e32 v[72:73], v[56:57]
	v_mov_b64_e32 v[70:71], v[54:55]
	v_mov_b64_e32 v[68:69], v[52:53]
	v_mov_b64_e32 v[66:67], v[50:51]
	v_mov_b64_e32 v[36:37], v[52:53]
	v_mov_b64_e32 v[38:39], v[54:55]
	v_mov_b64_e32 v[40:41], v[56:57]
	v_mov_b64_e32 v[42:43], v[58:59]
	v_mov_b64_e32 v[44:45], v[60:61]
	v_mov_b64_e32 v[46:47], v[62:63]
	v_mov_b64_e32 v[48:49], v[64:65]
	v_mov_b64_e32 v[20:21], v[52:53]
	v_mov_b64_e32 v[22:23], v[54:55]
	v_mov_b64_e32 v[24:25], v[56:57]
	v_mov_b64_e32 v[26:27], v[58:59]
	v_mov_b64_e32 v[28:29], v[60:61]
	v_mov_b64_e32 v[30:31], v[62:63]
	v_mov_b64_e32 v[32:33], v[64:65]
	v_readfirstlane_b32 s60, v204
	v_readfirstlane_b32 s61, v205
	v_readfirstlane_b32 s62, v206
	v_readfirstlane_b32 s63, v207
	v_mul_lo_u32 v248, v14, s84
	v_lshlrev_b32_e32 v247, 3, v14
	v_and_b32_e32 v247, 0x70, v247
	v_add_u32_e32 v249, 0x12000, v248
	v_add_u32_e32 v248, s19, v248
	v_xad_u32 v204, v247, v208, v249
	v_xad_u32 v206, v247, v229, v249
	v_xad_u32 v207, v247, v234, v249
	v_xad_u32 v211, v247, v235, v249
	v_xad_u32 v213, v247, v208, v248
	v_xad_u32 v215, v247, v229, v248
	v_xad_u32 v217, v247, v234, v248
	v_xad_u32 v245, v247, v235, v248
	v_readlane_b32 vcc_lo, v253, 43
	s_cmp_ge_u32 vcc_lo, 0x100
	s_cbranch_scc1 .Lmla_prio_hi
	s_setprio 1
.Lmla_prio_hi:
	s_waitcnt vmcnt(0) lgkmcnt(0)
	s_barrier

.LBB0_2205:
	s_setprio 0
	v_mov_b32_e32 v0, v14
	s_nop 0
	v_mul_lo_u32 v114, v0, s84
	v_lshlrev_b32_e32 v0, 3, v0
	v_add_u32_e32 v114, s24, v114
	v_and_b32_e32 v0, 0x70, v0
	v_xad_u32 v194, v0, v208, v114
	v_xad_u32 v195, v0, v229, v114
	v_xad_u32 v196, v0, v234, v114
	v_xad_u32 v0, v0, v235, v114
	ds_read_b128 v[114:117], v194 offset:0
	ds_read_b128 v[130:133], v194 offset:0x3000
	ds_read_b128 v[182:185], v195 offset:0
	ds_read_b128 v[186:189], v195 offset:0x3000
	s_nop 0
	s_waitcnt lgkmcnt(3)
	s_nop 0
	v_mfma_f32_32x32x16_bf16 v[114:129], v[114:117], v[178:181], 0
	ds_read_b128 v[190:193], v196 offset:0
	s_waitcnt lgkmcnt(3)
	s_nop 0
	v_mfma_f32_32x32x16_bf16 v[130:145], v[130:133], v[178:181], 0
	ds_read_b128 v[178:181], v196 offset:0x3000
	s_waitcnt lgkmcnt(3)
	s_nop 0
	v_mfma_f32_32x32x16_bf16 v[114:129], v[182:185], v[174:177], v[114:129]
	ds_read_b128 v[182:185], v0 offset:0
	s_waitcnt lgkmcnt(3)
	s_nop 0
	v_mfma_f32_32x32x16_bf16 v[130:145], v[186:189], v[174:177], v[130:145]
	ds_read_b128 v[174:177], v0 offset:0x3000
	s_waitcnt lgkmcnt(3)
	s_nop 0
	v_mfma_f32_32x32x16_bf16 v[114:129], v[190:193], v[170:173], v[114:129]
	ds_read_b128 v[186:189], v194 offset:0x80
	s_waitcnt lgkmcnt(3)
	s_nop 0
	v_mfma_f32_32x32x16_bf16 v[130:145], v[178:181], v[170:173], v[130:145]
	ds_read_b128 v[170:173], v194 offset:0x3080
	s_waitcnt lgkmcnt(3)
	s_nop 0
	v_mfma_f32_32x32x16_bf16 v[114:129], v[182:185], v[166:169], v[114:129]
	ds_read_b128 v[178:181], v195 offset:0x80
	s_waitcnt lgkmcnt(3)
	s_nop 0
	v_mfma_f32_32x32x16_bf16 v[130:145], v[174:177], v[166:169], v[130:145]
	ds_read_b128 v[166:169], v195 offset:0x3080
	s_waitcnt lgkmcnt(3)
	s_nop 0
	v_mfma_f32_32x32x16_bf16 v[114:129], v[186:189], v[162:165], v[114:129]
	ds_read_b128 v[174:177], v196 offset:0x80
	s_waitcnt lgkmcnt(3)
	s_nop 0
	v_mfma_f32_32x32x16_bf16 v[130:145], v[170:173], v[162:165], v[130:145]
	ds_read_b128 v[162:165], v196 offset:0x3080
	s_waitcnt lgkmcnt(3)
	s_nop 0
	v_mfma_f32_32x32x16_bf16 v[114:129], v[178:181], v[158:161], v[114:129]
	ds_read_b128 v[170:173], v0 offset:0x80
	s_waitcnt lgkmcnt(3)
	s_nop 0
	v_mfma_f32_32x32x16_bf16 v[130:145], v[166:169], v[158:161], v[130:145]
	ds_read_b128 v[158:161], v0 offset:0x3080
	s_waitcnt lgkmcnt(3)
	s_nop 0
	v_mfma_f32_32x32x16_bf16 v[114:129], v[174:177], v[154:157], v[114:129]
	ds_read_b128 v[166:169], v194 offset:0x100
	s_waitcnt lgkmcnt(3)
	s_nop 0
	v_mfma_f32_32x32x16_bf16 v[130:145], v[162:165], v[154:157], v[130:145]
	ds_read_b128 v[154:157], v194 offset:0x3100
	s_waitcnt lgkmcnt(3)
	s_nop 0
	v_mfma_f32_32x32x16_bf16 v[114:129], v[170:173], v[150:153], v[114:129]
	ds_read_b128 v[162:165], v195 offset:0x100
	s_waitcnt lgkmcnt(3)
	s_nop 0
	v_mfma_f32_32x32x16_bf16 v[130:145], v[158:161], v[150:153], v[130:145]
	ds_read_b128 v[150:153], v195 offset:0x3100
	s_waitcnt lgkmcnt(3)
	s_nop 0
	v_mfma_f32_32x32x16_bf16 v[114:129], v[166:169], v[146:149], v[114:129]
	ds_read_b128 v[158:161], v196 offset:0x100
	s_waitcnt lgkmcnt(3)
	s_nop 0
	v_mfma_f32_32x32x16_bf16 v[130:145], v[154:157], v[146:149], v[130:145]
	ds_read_b128 v[146:149], v196 offset:0x3100
	s_waitcnt lgkmcnt(3)
	s_nop 0
	v_mfma_f32_32x32x16_bf16 v[114:129], v[162:165], v[10:13], v[114:129]
	ds_read_b128 v[154:157], v0 offset:0x100
	s_waitcnt lgkmcnt(3)
	s_nop 0
	v_mfma_f32_32x32x16_bf16 v[130:145], v[150:153], v[10:13], v[130:145]
	ds_read_b128 v[10:13], v0 offset:0x3100
	s_waitcnt lgkmcnt(3)
	s_waitcnt lgkmcnt(2)
	s_waitcnt lgkmcnt(1)
	s_nop 0
	s_waitcnt lgkmcnt(0)
	v_mfma_f32_32x32x16_bf16 v[114:129], v[158:161], v[6:9], v[114:129]
	v_mfma_f32_32x32x16_bf16 v[130:145], v[146:149], v[6:9], v[130:145]
	v_mfma_f32_32x32x16_bf16 v[114:129], v[154:157], v[2:5], v[114:129]
	v_mfma_f32_32x32x16_bf16 v[130:145], v[10:13], v[2:5], v[130:145]
	v_add_f32_e32 v0, 0, v82
	v_add_f32_e32 v0, v83, v0
	v_add_f32_e32 v0, v84, v0
	v_add_f32_e32 v0, v85, v0
	v_add_f32_e32 v0, v86, v0
	v_add_f32_e32 v0, v87, v0
	v_add_f32_e32 v0, v88, v0
	v_add_f32_e32 v0, v89, v0
	v_add_f32_e32 v0, v90, v0
	v_add_f32_e32 v0, v91, v0
	v_add_f32_e32 v0, v92, v0
	v_add_f32_e32 v0, v93, v0
	v_exp_f32_e32 v3, v98
	v_add_f32_e32 v0, v94, v0
	v_exp_f32_e32 v12, v99
	v_add_f32_e32 v0, v95, v0
	v_exp_f32_e32 v13, v100
	v_add_f32_e32 v0, v96, v0
	v_exp_f32_e32 v98, v101
	v_add_f32_e32 v0, v97, v0
	v_exp_f32_e32 v99, v102
	v_add_f32_e32 v0, v3, v0
	v_exp_f32_e32 v100, v103
	v_add_f32_e32 v0, v12, v0
	v_exp_f32_e32 v101, v104
	v_add_f32_e32 v0, v13, v0
	v_exp_f32_e32 v102, v105
	v_add_f32_e32 v0, v98, v0
	v_exp_f32_e32 v103, v106
	v_add_f32_e32 v0, v99, v0
	v_exp_f32_e32 v104, v107
	v_add_f32_e32 v0, v100, v0
	v_exp_f32_e32 v105, v108
	v_add_f32_e32 v0, v101, v0
	v_exp_f32_e32 v106, v109
	v_add_f32_e32 v0, v102, v0
	v_exp_f32_e32 v107, v110
	v_add_f32_e32 v0, v103, v0
	v_exp_f32_e32 v108, v111
	v_add_f32_e32 v0, v104, v0
	v_exp_f32_e32 v109, v112
	v_add_f32_e32 v0, v105, v0
	v_exp_f32_e32 v110, v113
	v_add_f32_e32 v0, v106, v0
	v_add_f32_e32 v0, v107, v0
	v_add_f32_e32 v0, v108, v0
	v_add_f32_e32 v0, v109, v0
	v_add_f32_e32 v0, v110, v0
	v_mov_b32_e32 v2, v0
	s_nop 1
	v_permlane32_swap_b32_e32 v0, v2
	v_cvt_pk_bf16_f32 v4, v82, v83
	v_cvt_pk_bf16_f32 v5, v84, v85
	v_cvt_pk_bf16_f32 v6, v86, v87
	v_cvt_pk_bf16_f32 v7, v88, v89
	v_cvt_pk_bf16_f32 v8, v90, v91
	v_cvt_pk_bf16_f32 v9, v92, v93
	v_cvt_pk_bf16_f32 v10, v94, v95
	v_cvt_pk_bf16_f32 v11, v96, v97
	v_cvt_pk_bf16_f32 v82, v3, v12
	v_cvt_pk_bf16_f32 v83, v13, v98
	v_cvt_pk_bf16_f32 v84, v99, v100
	v_cvt_pk_bf16_f32 v85, v101, v102
	v_cvt_pk_bf16_f32 v86, v103, v104
	v_cvt_pk_bf16_f32 v87, v105, v106
	v_cvt_pk_bf16_f32 v88, v107, v108
	v_cvt_pk_bf16_f32 v89, v109, v110
	s_nop 0
	v_permlane32_swap_b32_e32 v4, v6
	v_permlane32_swap_b32_e32 v5, v7
	v_permlane32_swap_b32_e32 v8, v10
	v_permlane32_swap_b32_e32 v9, v11
	v_permlane32_swap_b32_e32 v82, v84
	v_permlane32_swap_b32_e32 v83, v85
	v_permlane32_swap_b32_e32 v86, v88
	v_permlane32_swap_b32_e32 v87, v89
	s_lshl_b32 s12, s26, 14
	v_add_u32_e32 v3, s12, v209
	ds_read_b64_tr_b16 v[90:91], v3 offset:0
	ds_read_b64_tr_b16 v[92:93], v3 offset:0x800
	ds_read_b64_tr_b16 v[94:95], v3 offset:0x1000
	ds_read_b64_tr_b16 v[96:97], v3 offset:0x1800
	ds_read_b64_tr_b16 v[98:99], v3 offset:0x2000
	ds_read_b64_tr_b16 v[100:101], v3 offset:0x2800
	ds_read_b64_tr_b16 v[102:103], v3 offset:0x3000
	ds_read_b64_tr_b16 v[104:105], v3 offset:0x3800
	s_waitcnt lgkmcnt(0)
	s_nop 0
	v_mfma_f32_32x32x16_bf16 v[50:65], v[4:7], v[90:93], v[50:65]
	ds_read_b64_tr_b16 v[90:91], v3 offset:0x200
	ds_read_b64_tr_b16 v[92:93], v3 offset:0xa00
	v_mfma_f32_32x32x16_bf16 v[50:65], v[8:11], v[94:97], v[50:65]
	ds_read_b64_tr_b16 v[94:95], v3 offset:0x1200
	ds_read_b64_tr_b16 v[96:97], v3 offset:0x1a00
	v_mfma_f32_32x32x16_bf16 v[50:65], v[82:85], v[98:101], v[50:65]
	ds_read_b64_tr_b16 v[98:99], v3 offset:0x2200
	ds_read_b64_tr_b16 v[100:101], v3 offset:0x2a00
	v_mfma_f32_32x32x16_bf16 v[50:65], v[86:89], v[102:105], v[50:65]
	ds_read_b64_tr_b16 v[102:103], v3 offset:0x3200
	ds_read_b64_tr_b16 v[104:105], v3 offset:0x3a00
	s_waitcnt lgkmcnt(0)
	v_mfma_f32_32x32x16_bf16 v[66:81], v[4:7], v[90:93], v[66:81]
	ds_read_b64_tr_b16 v[90:91], v3 offset:0x400
	ds_read_b64_tr_b16 v[92:93], v3 offset:0xc00
	v_mfma_f32_32x32x16_bf16 v[66:81], v[8:11], v[94:97], v[66:81]
	ds_read_b64_tr_b16 v[94:95], v3 offset:0x1400
	ds_read_b64_tr_b16 v[96:97], v3 offset:0x1c00
	v_mfma_f32_32x32x16_bf16 v[66:81], v[82:85], v[98:101], v[66:81]
	ds_read_b64_tr_b16 v[98:99], v3 offset:0x2400
	ds_read_b64_tr_b16 v[100:101], v3 offset:0x2c00
	v_mfma_f32_32x32x16_bf16 v[66:81], v[86:89], v[102:105], v[66:81]
	ds_read_b64_tr_b16 v[102:103], v3 offset:0x3400
	ds_read_b64_tr_b16 v[104:105], v3 offset:0x3c00
	s_waitcnt lgkmcnt(0)
	v_mfma_f32_32x32x16_bf16 v[34:49], v[4:7], v[90:93], v[34:49]
	ds_read_b64_tr_b16 v[90:91], v3 offset:0x600
	ds_read_b64_tr_b16 v[92:93], v3 offset:0xe00
	v_mfma_f32_32x32x16_bf16 v[34:49], v[8:11], v[94:97], v[34:49]
	ds_read_b64_tr_b16 v[94:95], v3 offset:0x1600
	ds_read_b64_tr_b16 v[96:97], v3 offset:0x1e00
	v_mfma_f32_32x32x16_bf16 v[34:49], v[82:85], v[98:101], v[34:49]
	ds_read_b64_tr_b16 v[98:99], v3 offset:0x2600
	ds_read_b64_tr_b16 v[100:101], v3 offset:0x2e00
	v_mfma_f32_32x32x16_bf16 v[34:49], v[86:89], v[102:105], v[34:49]
	ds_read_b64_tr_b16 v[102:103], v3 offset:0x3600
	ds_read_b64_tr_b16 v[104:105], v3 offset:0x3e00
	s_waitcnt lgkmcnt(0)
	v_mfma_f32_32x32x16_bf16 v[18:33], v[4:7], v[90:93], v[18:33]
	s_sub_i32 s2, 0x3fc0, s8
	s_sub_i32 s3, 0x3fff, s8
	s_cmp_le_i32 s3, s9
	s_cselect_b64 s[8:9], -1, 0
	s_cmp_gt_i32 s2, s11
	s_cselect_b64 s[14:15], -1, 0
	s_and_b64 s[8:9], s[8:9], s[14:15]
	v_mfma_f32_32x32x16_bf16 v[18:33], v[8:11], v[94:97], v[18:33]
	s_and_b64 vcc, exec, s[8:9]
	v_mfma_f32_32x32x16_bf16 v[18:33], v[82:85], v[98:101], v[18:33]
	v_mfma_f32_32x32x16_bf16 v[18:33], v[86:89], v[102:105], v[18:33]
	s_cbranch_vccnz .LBB0_2207
	v_subrev_u32_e32 v3, s2, v226
	v_cmp_gt_u32_e32 vcc, 2.0, v3
	v_subrev_u32_e32 v4, 32, v3
	s_nop 0
	v_cndmask_b32_e32 v114, v16, v114, vcc
	v_cmp_gt_u32_e32 vcc, 2.0, v4
	v_add_u32_e32 v4, -1, v3
	s_nop 0
	v_cndmask_b32_e32 v130, v16, v130, vcc
	v_cmp_gt_u32_e32 vcc, 2.0, v4
	v_subrev_u32_e32 v4, 33, v3
	s_nop 0
	v_cndmask_b32_e32 v115, v16, v115, vcc
	v_cmp_gt_u32_e32 vcc, 2.0, v4
	v_add_u32_e32 v4, -2, v3
	s_nop 0
	v_cndmask_b32_e32 v131, v16, v131, vcc
	v_cmp_gt_u32_e32 vcc, 2.0, v4
	v_subrev_u32_e32 v4, 34, v3
	s_nop 0
	v_cndmask_b32_e32 v116, v16, v116, vcc
	v_cmp_gt_u32_e32 vcc, 2.0, v4
	v_add_u32_e32 v4, -3, v3
	s_nop 0
	v_cndmask_b32_e32 v132, v16, v132, vcc
	v_cmp_gt_u32_e32 vcc, 2.0, v4
	v_subrev_u32_e32 v4, 35, v3
	s_nop 0
	v_cndmask_b32_e32 v117, v16, v117, vcc
	v_cmp_gt_u32_e32 vcc, 2.0, v4
	v_add_u32_e32 v4, -8, v3
	s_nop 0
	v_cndmask_b32_e32 v133, v16, v133, vcc
	v_cmp_gt_u32_e32 vcc, 2.0, v4
	v_subrev_u32_e32 v4, 40, v3
	s_nop 0
	v_cndmask_b32_e32 v118, v16, v118, vcc
	v_cmp_gt_u32_e32 vcc, 2.0, v4
	v_add_u32_e32 v4, -9, v3
	s_nop 0
	v_cndmask_b32_e32 v134, v16, v134, vcc
	v_cmp_gt_u32_e32 vcc, 2.0, v4
	v_subrev_u32_e32 v4, 41, v3
	s_nop 0
	v_cndmask_b32_e32 v119, v16, v119, vcc
	v_cmp_gt_u32_e32 vcc, 2.0, v4
	v_add_u32_e32 v4, -10, v3
	s_nop 0
	v_cndmask_b32_e32 v135, v16, v135, vcc
	v_cmp_gt_u32_e32 vcc, 2.0, v4
	v_subrev_u32_e32 v4, 42, v3
	s_nop 0
	v_cndmask_b32_e32 v120, v16, v120, vcc
	v_cmp_gt_u32_e32 vcc, 2.0, v4
	v_add_u32_e32 v4, -11, v3
	s_nop 0
	v_cndmask_b32_e32 v136, v16, v136, vcc
	v_cmp_gt_u32_e32 vcc, 2.0, v4
	v_subrev_u32_e32 v4, 43, v3
	s_nop 0
	v_cndmask_b32_e32 v121, v16, v121, vcc
	v_cmp_gt_u32_e32 vcc, 2.0, v4
	v_add_u32_e32 v4, -16, v3
	s_nop 0
	v_cndmask_b32_e32 v137, v16, v137, vcc
	v_cmp_gt_u32_e32 vcc, 2.0, v4
	v_subrev_u32_e32 v4, 48, v3
	s_nop 0
	v_cndmask_b32_e32 v122, v16, v122, vcc
	v_cmp_gt_u32_e32 vcc, 2.0, v4
	v_subrev_u32_e32 v4, 17, v3
	s_nop 0
	v_cndmask_b32_e32 v138, v16, v138, vcc
	v_cmp_gt_u32_e32 vcc, 2.0, v4
	v_subrev_u32_e32 v4, 49, v3
	s_nop 0
	v_cndmask_b32_e32 v123, v16, v123, vcc
	v_cmp_gt_u32_e32 vcc, 2.0, v4
	v_subrev_u32_e32 v4, 18, v3
	s_nop 0
	v_cndmask_b32_e32 v139, v16, v139, vcc
	v_cmp_gt_u32_e32 vcc, 2.0, v4
	v_subrev_u32_e32 v4, 50, v3
	s_nop 0
	v_cndmask_b32_e32 v124, v16, v124, vcc
	v_cmp_gt_u32_e32 vcc, 2.0, v4
	v_subrev_u32_e32 v4, 19, v3
	s_nop 0
	v_cndmask_b32_e32 v140, v16, v140, vcc
	v_cmp_gt_u32_e32 vcc, 2.0, v4
	v_subrev_u32_e32 v4, 51, v3
	s_nop 0
	v_cndmask_b32_e32 v125, v16, v125, vcc
	v_cmp_gt_u32_e32 vcc, 2.0, v4
	v_subrev_u32_e32 v4, 24, v3
	s_nop 0
	v_cndmask_b32_e32 v141, v16, v141, vcc
	v_cmp_gt_u32_e32 vcc, 2.0, v4
	v_subrev_u32_e32 v4, 56, v3
	s_nop 0
	v_cndmask_b32_e32 v126, v16, v126, vcc
	v_cmp_gt_u32_e32 vcc, 2.0, v4
	v_subrev_u32_e32 v4, 25, v3
	s_nop 0
	v_cndmask_b32_e32 v142, v16, v142, vcc
	v_cmp_gt_u32_e32 vcc, 2.0, v4
	v_subrev_u32_e32 v4, 57, v3
	s_nop 0
	v_cndmask_b32_e32 v127, v16, v127, vcc
	v_cmp_gt_u32_e32 vcc, 2.0, v4
	v_subrev_u32_e32 v4, 26, v3
	s_nop 0
	v_cndmask_b32_e32 v143, v16, v143, vcc
	v_cmp_gt_u32_e32 vcc, 2.0, v4
	v_subrev_u32_e32 v4, 58, v3
	s_nop 0
	v_cndmask_b32_e32 v128, v16, v128, vcc
	v_cmp_gt_u32_e32 vcc, 2.0, v4
	v_subrev_u32_e32 v4, 27, v3
	v_subrev_u32_e32 v3, 59, v3
	v_cndmask_b32_e32 v144, v16, v144, vcc
	v_cmp_gt_u32_e32 vcc, 2.0, v4
	s_nop 1
	v_cndmask_b32_e32 v129, v16, v129, vcc
	v_cmp_gt_u32_e32 vcc, 2.0, v3
	s_nop 1
	v_cndmask_b32_e32 v145, v16, v145, vcc
